# start stagger applied to every workgroup with a round of slack (no bit test): only the workgroups with the extra unit start on time
# baseline (speedup 1.0000x reference)
; __global__ void __launch_bounds__(NWAVES * 64, 2) hymba_fwd(Args A) {
;     ...
;     {
;         pg8::Gemm g{(const pg8::bf16_t*)(ws + WS_XA), (const pg8::bf16_t*)(ws + WS_W1), M1, DIN, DM, DM};
;         pg8::StaticOrder S; S.init(M1, DIN, G, bx);
;         pg8::Epi1 E{(const float*)(ws + WS_RS1), (const float*)(ws + WS_ROPE), A.out, (pg8::bf16_t*)(ws + WS_QD), (pg8::bf16_t*)(ws + WS_QS), (pg8::bf16_t*)(ws + WS_KD), (pg8::bf16_t*)(ws + WS_KS),
;                     (pg8::bf16_t*)(ws + WS_VDT), (pg8::bf16_t*)(ws + WS_VST)};
;         pg8::gemm_phase<pg8::Epi1, pg8::StaticOrder, true, true>(lds, g, S, E);
.LBB0_102:
	s_or_b64 exec, exec, s[0:1]
	s_barrier
	s_cmp_lt_u32 s22, 36
	s_cbranch_scc1 .Lstag_p1
	s_nop 0
	s_sleep 127
	s_sleep 127
	s_sleep 127

; __global__ void __launch_bounds__(NWAVES * 64, 2) hymba_fwd(Args A) {
;     ...
;     xcd_barrier(bar);
;     {
;         pg8::Gemm g{(const pg8::bf16_t*)(ws + WS_X1B), (const pg8::bf16_t*)(ws + WS_W3), M2, DFF, DM, DM};
;         pg8::StaticOrder S; S.init(M2, DFF, G, bx);
;         pg8::Epi3 E{(const float*)(ws + WS_SS2), (pg8::bf16_t*)(ws + WS_H)};
;         pg8::gemm_phase<pg8::Epi3, pg8::StaticOrder, true, true>(lds, g, S, E);
.LBB0_746:
	s_or_b64 exec, exec, s[0:1]
	v_mov_b32_e32 v9, v138
	s_waitcnt lgkmcnt(0)
	s_barrier
	s_cmp_lt_u32 s22, 32
	s_cbranch_scc1 .Lstag_p4
	s_nop 0
	s_sleep 127
	s_sleep 127
	s_sleep 127
